# v10 with 4 (instead of 3) PV MFMAs of the odd tile deferred across the workgroup barrier
# baseline (speedup 1.0000x reference)
; #define LAS __attribute__((address_space(3)))
; __device__ __forceinline__ void mla_attn_phase(LAS unsigned char* lds, const bf16_t* q, const bf16_t* kv, const bf16_t* krope, const bf16_t* projb, bf16_t* y, int unit0, int G, int nu) {
;     ...
;     MLA_FETCH(unit);
;   for (;;) {
;     const int qb = unit & 15, h = (unit >> 4) & 15, s = unit >> 8;
;     const size_t row0 = (size_t)s * SEQ;
;     sb0 = *(const u32x4*)(src_kv + (size_t)192 * KVW); sb1 = *(const u32x4*)(src_kv + (size_t)224 * KVW); sb2 = *(const u32x4*)(src_r + (size_t)192 * 32);
; #pragma unroll
;     for (int t0 = 0; t0 < 3; ++t0) {
;         *(LAS u32x4*)(lds + t0 * MLA_BUF + dst_kv) = pre[3 * t0]; *(LAS u32x4*)(lds + t0 * MLA_BUF + dst_kv + dst_kv_step) = pre[3 * t0 + 1]; *(LAS u32x4*)(lds + ((tid < 256) ? t0 * MLA_BUF : 0) + dst_r) = pre[3 * t0 + 2];
;     }
;     __syncthreads();
;     f32x16 o0 = {0.f, 0.f, 0.f, 0.f, 0.f, 0.f, 0.f, 0.f, 0.f, 0.f, 0.f, 0.f, 0.f, 0.f, 0.f, 0.f}, o1 = o0, negm = o0;
;     const int voff = (4 * hi + ((lane & 15) >> 2)) * MLA_VS + (16 * ((lane >> 4) & 1) + 4 * (lane & 3)) * 2;
;     f32x16 c0, c1, n0, n1; u32x4 pa[4];
;     float m, lsum = 0.f;
;     MLA_QK(c0, c1, lds, negm);
;     { float tm; MLA_ROWMAX(c0, c1, tm); m = tm;
; #pragma unroll
;       for (int rr = 0; rr < 16; ++rr) { c0[rr] -= m; c1[rr] -= m; negm[rr] = -m; } }
;     int sl_c = 0, sl_n = MLA_BUF, sl_2 = 2 * MLA_BUF, sl_w = 3 * MLA_BUF, sl_4 = 4 * MLA_BUF;
.LBB0_201:
	s_mov_b32 s3, 0xc0000
	v_add_co_u32_e32 v0, vcc, s3, v206
	s_mov_b32 s3, 0xe0000
	s_nop 0
	v_addc_co_u32_e32 v1, vcc, 0, v207, vcc
	v_add_co_u32_e32 v2, vcc, s3, v206
	s_movk_i32 s3, 0x3000
	s_nop 0
	v_addc_co_u32_e32 v3, vcc, 0, v207, vcc
	global_load_dwordx4 v[152:155], v[0:1], off
	global_load_dwordx4 v[156:159], v[2:3], off
	v_add_co_u32_e32 v0, vcc, s3, v208
	v_add_u32_e32 v201, v185, v181
	s_nop 0
	v_addc_co_u32_e32 v1, vcc, 0, v209, vcc
	global_load_dwordx4 v[160:163], v[0:1], off
	s_waitcnt vmcnt(11)
	ds_write_b128 v185, v[32:35]
	s_waitcnt vmcnt(9)
	ds_write_b128 v201, v[40:43]
	ds_write_b128 v214, v[36:39]
	s_waitcnt vmcnt(8)
	ds_write_b128 v185, v[44:47] offset:25600
	s_waitcnt vmcnt(7)
	ds_write_b128 v201, v[48:51] offset:25600
	s_waitcnt vmcnt(4)
	ds_write_b128 v246, v[64:67]
	ds_write_b128 v185, v[52:55] offset:51200
	ds_write_b128 v201, v[56:59] offset:51200
	s_waitcnt vmcnt(3)
	ds_write_b128 v247, v[60:63]
	s_waitcnt lgkmcnt(0)
	s_barrier
	ds_read_b128 v[0:3], v215
	ds_read_b128 v[4:7], v215 offset:32
	s_waitcnt lgkmcnt(1)
	v_mfma_f32_32x32x16_bf16 v[32:47], v[0:3], v[148:151], 0
	ds_read_b128 v[0:3], v215 offset:6656
	ds_read_b128 v[8:11], v215 offset:6688
	s_mov_b32 s8, 0
	s_mov_b32 s9, s8
	s_mov_b32 s10, s8
	s_mov_b32 s11, s8
	s_mov_b32 s12, s8
	s_mov_b32 s13, s8
	s_waitcnt lgkmcnt(1)
	v_mfma_f32_32x32x16_bf16 v[16:31], v[0:3], v[148:151], 0
	s_mov_b32 s14, s8
	s_mov_b32 s15, s8
	s_mov_b32 s16, s8
	s_mov_b32 s17, s8
	s_mov_b32 s18, s8
	s_mov_b32 s19, s8
	s_mov_b32 s20, s8
	v_mfma_f32_32x32x16_bf16 v[32:47], v[4:7], v[144:147], v[32:47]
	ds_read_b128 v[0:3], v215 offset:64
	ds_read_b128 v[4:7], v215 offset:96
	s_mov_b32 s21, s8
	s_mov_b32 s22, s8
	s_mov_b32 s23, s8
	s_mov_b32 s3, 0x19000
	s_mov_b32 s6, 0x12c00
	s_mov_b32 s7, 0xc800
	s_waitcnt lgkmcnt(2)
	v_mfma_f32_32x32x16_bf16 v[16:31], v[8:11], v[144:147], v[16:31]
	v_mov_b32_e32 v205, 0
	s_waitcnt lgkmcnt(1)
	v_mfma_f32_32x32x16_bf16 v[32:47], v[0:3], v[140:143], v[32:47]
	ds_read_b128 v[0:3], v215 offset:6720
	ds_read_b128 v[8:11], v215 offset:6752
	s_waitcnt lgkmcnt(1)
	v_mfma_f32_32x32x16_bf16 v[16:31], v[0:3], v[140:143], v[16:31]
	v_mfma_f32_32x32x16_bf16 v[32:47], v[4:7], v[136:139], v[32:47]
	s_waitcnt lgkmcnt(0)
	v_mfma_f32_32x32x16_bf16 v[16:31], v[8:11], v[136:139], v[16:31]
	ds_read_b128 v[0:3], v215 offset:128
	ds_read_b128 v[4:7], v215 offset:6784
	ds_read_b128 v[8:11], v215 offset:160
	ds_read_b128 v[48:51], v215 offset:6816
	s_waitcnt lgkmcnt(3)
	v_mfma_f32_32x32x16_bf16 v[32:47], v[0:3], v[132:135], v[32:47]
	s_waitcnt lgkmcnt(2)
	v_mfma_f32_32x32x16_bf16 v[16:31], v[4:7], v[132:135], v[16:31]
	s_waitcnt lgkmcnt(1)
	v_mfma_f32_32x32x16_bf16 v[32:47], v[8:11], v[128:131], v[32:47]
	v_mov_b64_e32 v[0:1], s[8:9]
	v_mov_b64_e32 v[14:15], s[22:23]
	v_mov_b64_e32 v[2:3], s[10:11]
	v_mov_b64_e32 v[4:5], s[12:13]
	v_mov_b64_e32 v[6:7], s[14:15]
	v_mov_b64_e32 v[8:9], s[16:17]
	v_mov_b64_e32 v[10:11], s[18:19]
	s_waitcnt lgkmcnt(0)
	v_mfma_f32_32x32x16_bf16 v[16:31], v[48:51], v[128:131], v[16:31]
	s_nop 2
	v_max_f32_e32 v52, v33, v33
	v_max_f32_e32 v53, v32, v32
	v_max_f32_e32 v52, v53, v52
	v_mov_b64_e32 v[12:13], s[20:21]
	s_movk_i32 s12, 0x6400
	s_mov_b32 s9, -2
	s_nop 2
	v_max3_f32 v48, v34, v35, v17
	v_max3_f32 v49, v52, v16, v18
	v_max3_f32 v49, v49, v19, v36
	v_max3_f32 v48, v48, v38, v39
	v_max3_f32 v49, v49, v37, v20
	v_max3_f32 v48, v48, v22, v23
	v_max3_f32 v49, v49, v21, v40
	v_max3_f32 v48, v48, v42, v43
	v_max3_f32 v49, v49, v41, v24
	v_max3_f32 v48, v48, v26, v27
	v_max3_f32 v49, v49, v25, v44
	v_max3_f32 v48, v48, v46, v47
	v_max3_f32 v49, v49, v45, v28
	v_max3_f32 v48, v48, v30, v31
	v_max3_f32 v48, v49, v29, v48
	v_mov_b32_e32 v49, v48
	s_nop 1
	v_permlane32_swap_b32_e32 v48, v49
	v_max_f32_e32 v49, v49, v49
	v_max_f32_e32 v48, v48, v48
	v_max_f32_e32 v203, v48, v49
	v_xor_b32_e32 v48, 0x80000000, v203
	v_sub_f32_e32 v111, v31, v203
	v_sub_f32_e32 v110, v30, v203
	v_sub_f32_e32 v109, v29, v203
	v_sub_f32_e32 v108, v28, v203
	v_sub_f32_e32 v107, v27, v203
	v_sub_f32_e32 v106, v26, v203
	v_sub_f32_e32 v105, v25, v203
	v_sub_f32_e32 v104, v24, v203
	v_sub_f32_e32 v103, v23, v203
	v_sub_f32_e32 v102, v22, v203
	v_sub_f32_e32 v101, v21, v203
	v_sub_f32_e32 v100, v20, v203
	v_sub_f32_e32 v99, v19, v203
	v_sub_f32_e32 v98, v18, v203
	v_sub_f32_e32 v97, v17, v203
	v_sub_f32_e32 v96, v16, v203
	v_mov_b64_e32 v[30:31], v[14:15]
	v_sub_f32_e32 v95, v47, v203
	v_sub_f32_e32 v94, v46, v203
	v_sub_f32_e32 v93, v45, v203
	v_sub_f32_e32 v92, v44, v203
	v_sub_f32_e32 v91, v43, v203
	v_sub_f32_e32 v90, v42, v203
	v_sub_f32_e32 v89, v41, v203
	v_sub_f32_e32 v88, v40, v203
	v_sub_f32_e32 v87, v39, v203
	v_sub_f32_e32 v86, v38, v203
	v_sub_f32_e32 v85, v37, v203
	v_sub_f32_e32 v84, v36, v203
	v_sub_f32_e32 v83, v35, v203
	v_sub_f32_e32 v82, v34, v203
	v_sub_f32_e32 v81, v33, v203
	v_sub_f32_e32 v80, v32, v203
	v_mov_b64_e32 v[28:29], v[12:13]
	v_mov_b64_e32 v[26:27], v[10:11]
	v_mov_b64_e32 v[24:25], v[8:9]
	v_mov_b64_e32 v[22:23], v[6:7]
	v_mov_b64_e32 v[20:21], v[4:5]
	v_mov_b64_e32 v[18:19], v[2:3]
	v_mov_b64_e32 v[16:17], v[0:1]
	v_mov_b32_e32 v49, v48
	v_mov_b32_e32 v50, v48
	v_mov_b32_e32 v51, v48
	v_mov_b32_e32 v52, v48
	v_mov_b32_e32 v53, v48
	v_mov_b32_e32 v54, v48
	v_mov_b32_e32 v55, v48
	v_mov_b32_e32 v56, v48
	v_mov_b32_e32 v57, v48
	v_mov_b32_e32 v58, v48
	v_mov_b32_e32 v59, v48
	v_mov_b32_e32 v60, v48
	v_mov_b32_e32 v61, v48
	v_mov_b32_e32 v62, v48
	v_mov_b32_e32 v63, v48
	v_mov_b32_e32 v64, 0
	v_mov_b32_e32 v65, 0
	v_mov_b32_e32 v66, 0
	v_mov_b32_e32 v67, 0
	v_mov_b32_e32 v72, 0
	v_mov_b32_e32 v73, 0
	v_mov_b32_e32 v74, 0
	v_mov_b32_e32 v75, 0
	v_mov_b32_e32 v36, 0
	v_mov_b32_e32 v37, 0
	v_mov_b32_e32 v38, 0
	v_mov_b32_e32 v39, 0
	v_mov_b32_e32 v40, 0
	v_mov_b32_e32 v41, 0
	v_mov_b32_e32 v42, 0
	v_mov_b32_e32 v43, 0
	v_mov_b32_e32 v44, 0
	v_mov_b32_e32 v45, 0
	v_mov_b32_e32 v46, 0
	v_mov_b32_e32 v47, 0
	v_mov_b32_e32 v238, 0
	v_mov_b32_e32 v239, 0
	v_mov_b32_e32 v240, 0
	v_mov_b32_e32 v241, 0
; __device__ __forceinline__ void mla_attn_phase(LAS unsigned char* lds, const bf16_t* q, const bf16_t* kv, const bf16_t* krope, const bf16_t* projb, bf16_t* y, int unit0, int G, int nu) {
;     ...
; #pragma unroll 1
;     for (int t = 0; t < 62; t += 2) {
;         MLA_ITER(t, c0, c1, n0, n1, sa0, sa1, sa2, sb0, sb1, sb2, false);
;         MLA_ITER(t + 1, n0, n1, c0, c1, sb0, sb1, sb2, sa0, sa1, sa2, true);
.LBB0_202:
	s_add_i32 s9, s9, 2
	s_mov_b32 s11, s8
	s_mov_b32 s10, s12
	v_add_u32_e32 v242, s10, v215
	ds_read_b128 v[32:35], v242
	v_mfma_f32_32x32x16_bf16 v[0:15], v[64:67], v[36:39], v[0:15]
	ds_read_b128 v[36:39], v242 offset:6656
	v_mfma_f32_32x32x16_bf16 v[16:31], v[64:67], v[40:43], v[16:31]
	ds_read_b128 v[40:43], v242 offset:32
	v_mfma_f32_32x32x16_bf16 v[0:15], v[72:75], v[44:47], v[0:15]
	ds_read_b128 v[44:47], v242 offset:6688
	v_mfma_f32_32x32x16_bf16 v[16:31], v[72:75], v[238:241], v[16:31]
	ds_read_b128 v[238:241], v242 offset:64
	v_add_u32_e32 v243, s11, v233
	s_min_u32 s8, s9, 59
	s_lshl_b32 s8, s8, 6
	s_addk_i32 s8, 0x100
	s_lshl_b32 s76, s8, 12
	v_lshl_add_u64 v[164:165], v[206:207], 0, s[76:77]
	v_add_co_u32_e32 v172, vcc, s83, v164
	s_lshl_b32 s76, s8, 6
	s_nop 0
	v_addc_co_u32_e32 v173, vcc, 0, v165, vcc
	global_load_dwordx4 v[164:167], v[164:165], off
	v_lshl_add_u64 v[168:169], v[208:209], 0, s[76:77]
	global_load_dwordx4 v[172:175], v[172:173], off
	global_load_dwordx4 v[168:171], v[168:169], off
	v_exp_f32_e32 v80, v80
	v_exp_f32_e32 v81, v81
	v_exp_f32_e32 v82, v82
	v_add_f32_e32 v205, v205, v80
	v_exp_f32_e32 v83, v83
	v_exp_f32_e32 v84, v84
	v_add_f32_e32 v205, v205, v82
	v_exp_f32_e32 v85, v85
	v_add_f32_e32 v252, v81, v83
	v_exp_f32_e32 v86, v86
	v_exp_f32_e32 v87, v87
	v_exp_f32_e32 v88, v88
	v_exp_f32_e32 v89, v89
	v_cvt_pk_bf16_f32 v80, v80, v81
	v_cvt_pk_bf16_f32 v81, v82, v83
	v_cvt_pk_bf16_f32 v82, v84, v85
	v_cvt_pk_bf16_f32 v83, v86, v87
	v_exp_f32_e32 v90, v90
	v_add_f32_e32 v205, v205, v88
	v_exp_f32_e32 v91, v91
	v_add_f32_e32 v252, v252, v89
	v_exp_f32_e32 v92, v92
	v_add_f32_e32 v205, v205, v90
	v_exp_f32_e32 v93, v93
	v_add_f32_e32 v252, v252, v91
	v_exp_f32_e32 v94, v94
	v_exp_f32_e32 v95, v95
	v_exp_f32_e32 v96, v96
	v_exp_f32_e32 v97, v97
	v_cvt_pk_bf16_f32 v88, v88, v89
	s_waitcnt lgkmcnt(3)
	v_mfma_f32_32x32x16_bf16 v[112:127], v[32:35], v[148:151], v[48:63]
	ds_read_b128 v[32:35], v242 offset:6720
	v_cvt_pk_bf16_f32 v89, v90, v91
	v_cvt_pk_bf16_f32 v90, v92, v93
	v_cvt_pk_bf16_f32 v91, v94, v95
	v_mfma_f32_32x32x16_bf16 v[64:79], v[36:39], v[148:151], v[48:63]
	ds_read_b128 v[36:39], v242 offset:96
	v_exp_f32_e32 v98, v98
	v_add_f32_e32 v205, v205, v96
	v_exp_f32_e32 v99, v99
	s_waitcnt lgkmcnt(3)
	v_mfma_f32_32x32x16_bf16 v[112:127], v[40:43], v[144:147], v[112:127]
	ds_read_b128 v[40:43], v242 offset:6752
	v_add_f32_e32 v252, v252, v97
	v_exp_f32_e32 v100, v100
	v_add_f32_e32 v205, v205, v98
	v_mfma_f32_32x32x16_bf16 v[64:79], v[44:47], v[144:147], v[64:79]
	ds_read_b128 v[44:47], v242 offset:128
	v_exp_f32_e32 v101, v101
	v_add_f32_e32 v252, v252, v99
	v_exp_f32_e32 v102, v102
	s_waitcnt lgkmcnt(3)
	v_mfma_f32_32x32x16_bf16 v[112:127], v[238:241], v[140:143], v[112:127]
	ds_read_b128 v[238:241], v242 offset:6784
	v_exp_f32_e32 v103, v103
	v_exp_f32_e32 v104, v104
	v_exp_f32_e32 v105, v105
	v_mfma_f32_32x32x16_bf16 v[64:79], v[32:35], v[140:143], v[64:79]
	ds_read_b128 v[32:35], v242 offset:160
	v_cvt_pk_bf16_f32 v96, v96, v97
	v_cvt_pk_bf16_f32 v97, v98, v99
	v_cvt_pk_bf16_f32 v98, v100, v101
	s_waitcnt lgkmcnt(3)
	v_mfma_f32_32x32x16_bf16 v[112:127], v[36:39], v[136:139], v[112:127]
	ds_read_b128 v[36:39], v242 offset:6816
	v_cvt_pk_bf16_f32 v99, v102, v103
	v_exp_f32_e32 v106, v106
	v_add_f32_e32 v205, v205, v104
	v_mfma_f32_32x32x16_bf16 v[64:79], v[40:43], v[136:139], v[64:79]
	ds_read_b64_tr_b16 v[40:41], v243 offset:13312
	ds_read_b64_tr_b16 v[42:43], v243 offset:14848
	v_exp_f32_e32 v107, v107
	v_add_f32_e32 v252, v252, v105
	v_exp_f32_e32 v108, v108
	s_waitcnt lgkmcnt(4)
	v_mfma_f32_32x32x16_bf16 v[112:127], v[44:47], v[132:135], v[112:127]
	ds_read_b64_tr_b16 v[44:45], v243 offset:13376
	ds_read_b64_tr_b16 v[46:47], v243 offset:14912
	v_add_f32_e32 v205, v205, v106
	v_exp_f32_e32 v109, v109
	v_add_f32_e32 v252, v252, v107
	v_mfma_f32_32x32x16_bf16 v[64:79], v[238:241], v[132:135], v[64:79]
	ds_read_b64_tr_b16 v[238:239], v243 offset:16384
	ds_read_b64_tr_b16 v[240:241], v243 offset:17920
	v_exp_f32_e32 v110, v110
	v_exp_f32_e32 v111, v111
	v_cvt_pk_bf16_f32 v104, v104, v105
	s_waitcnt lgkmcnt(6)
	v_mfma_f32_32x32x16_bf16 v[112:127], v[32:35], v[128:131], v[112:127]
	ds_read_b64_tr_b16 v[32:33], v243 offset:16448
	ds_read_b64_tr_b16 v[34:35], v243 offset:17984
	v_cvt_pk_bf16_f32 v105, v106, v107
	v_cvt_pk_bf16_f32 v106, v108, v109
	v_mfma_f32_32x32x16_bf16 v[64:79], v[36:39], v[128:131], v[64:79]
	ds_read_b64_tr_b16 v[36:37], v243 offset:19456
	ds_read_b64_tr_b16 v[38:39], v243 offset:20992
	v_cvt_pk_bf16_f32 v107, v110, v111
	s_waitcnt lgkmcnt(6)
	v_mfma_f32_32x32x16_bf16 v[0:15], v[80:83], v[40:43], v[0:15]
	ds_read_b64_tr_b16 v[40:41], v243 offset:19520
	ds_read_b64_tr_b16 v[42:43], v243 offset:21056
	v_add_f32_e32 v205, v205, v84
	v_add_f32_e32 v252, v252, v85
	v_add_f32_e32 v205, v205, v86
	v_add_f32_e32 v252, v252, v87
	v_mfma_f32_32x32x16_bf16 v[16:31], v[80:83], v[44:47], v[16:31]
	ds_read_b64_tr_b16 v[44:45], v243 offset:22528
	ds_read_b64_tr_b16 v[46:47], v243 offset:24064
	v_add_f32_e32 v205, v205, v92
	v_add_f32_e32 v252, v252, v93
	v_add_f32_e32 v205, v205, v94
	v_add_f32_e32 v252, v252, v95
	s_waitcnt lgkmcnt(6)
	v_mfma_f32_32x32x16_bf16 v[0:15], v[88:91], v[238:241], v[0:15]
	ds_read_b64_tr_b16 v[238:239], v243 offset:22592
	ds_read_b64_tr_b16 v[240:241], v243 offset:24128
	v_max_f32_e32 v191, v112, v113
	v_max_f32_e32 v178, v64, v65
	v_max3_f32 v191, v191, v114, v115
	v_add_f32_e32 v205, v205, v100
	v_add_f32_e32 v252, v252, v101
	v_mfma_f32_32x32x16_bf16 v[16:31], v[88:91], v[32:35], v[16:31]
	v_add_u32_e32 v242, s7, v215
	ds_read_b128 v[32:35], v242
	v_max3_f32 v178, v178, v66, v67
	v_max3_f32 v191, v191, v116, v117
	v_max3_f32 v178, v178, v68, v69
	v_add_f32_e32 v205, v205, v102
	v_add_f32_e32 v252, v252, v103
	s_waitcnt lgkmcnt(5)
	v_mfma_f32_32x32x16_bf16 v[0:15], v[96:99], v[36:39], v[0:15]
	ds_read_b128 v[36:39], v242 offset:6656
	v_max3_f32 v191, v191, v118, v119
	v_max3_f32 v178, v178, v70, v71
	v_max3_f32 v191, v191, v120, v121
	v_add_f32_e32 v205, v205, v108
	v_add_f32_e32 v252, v252, v109
	v_add_u32_e32 v177, s6, v185
	s_waitcnt vmcnt(5)
	ds_write_b128 v177, v[152:155]
	v_mfma_f32_32x32x16_bf16 v[16:31], v[96:99], v[40:43], v[16:31]
	ds_read_b128 v[40:43], v242 offset:32
	v_max3_f32 v178, v178, v72, v73
	v_max3_f32 v191, v191, v122, v123
	v_max3_f32 v178, v178, v74, v75
	v_add_f32_e32 v205, v205, v110
	v_add_f32_e32 v252, v252, v111
	v_add_u32_e32 v177, v177, v181
	s_waitcnt vmcnt(4)
	ds_write_b128 v177, v[156:159]
	s_waitcnt lgkmcnt(5)
	v_mfma_f32_32x32x16_bf16 v[0:15], v[104:107], v[44:47], v[0:15]
	ds_read_b128 v[44:47], v242 offset:6688
	v_max3_f32 v191, v191, v124, v125
	v_max3_f32 v178, v178, v76, v77
	v_max3_f32 v191, v191, v126, v127
	v_add_f32_e32 v205, v205, v252
	v_mov_b32_e32 v177, s6
	v_cndmask_b32_e64 v177, 0, v177, s[4:5]
	v_add_u32_e32 v177, v214, v177
	s_waitcnt vmcnt(3)
	ds_write_b128 v177, v[160:163]
	v_mfma_f32_32x32x16_bf16 v[16:31], v[104:107], v[238:241], v[16:31]
	ds_read_b128 v[238:241], v242 offset:64
	v_max3_f32 v178, v178, v78, v79
	v_max_f32_e32 v212, v191, v178
	v_mov_b32_e32 v253, v212
	s_min_u32 s8, s9, 58
	s_lshl_b32 s8, s8, 6
	s_addk_i32 s8, 0x140
	s_lshl_b32 s76, s8, 12
	v_lshl_add_u64 v[152:153], v[206:207], 0, s[76:77]
	v_add_co_u32_e32 v156, vcc, s83, v152
	s_lshl_b32 s76, s8, 6
	s_nop 0
	v_addc_co_u32_e32 v157, vcc, 0, v153, vcc
	global_load_dwordx4 v[152:155], v[152:153], off
	v_lshl_add_u64 v[160:161], v[208:209], 0, s[76:77]
	global_load_dwordx4 v[156:159], v[156:157], off
	global_load_dwordx4 v[160:163], v[160:161], off
	s_nop 1
	v_permlane32_swap_b32_e32 v212, v253
	v_max_f32_e32 v212, v212, v253
	v_cmp_lt_f32_e32 vcc, s58, v212
	s_cbranch_vccnz .Lmla_skip_a_ool
.Lmla_skip_a:
	v_add_u32_e32 v243, s10, v233
	s_waitcnt lgkmcnt(6)
	v_mfma_f32_32x32x16_bf16 v[80:95], v[32:35], v[148:151], v[48:63]
	ds_read_b128 v[32:35], v242 offset:6720
	v_exp_f32_e32 v112, v112
	v_exp_f32_e32 v113, v113
	v_exp_f32_e32 v114, v114
	v_add_f32_e32 v205, v205, v112
	v_exp_f32_e32 v115, v115
	v_mfma_f32_32x32x16_bf16 v[96:111], v[36:39], v[148:151], v[48:63]
	ds_read_b128 v[36:39], v242 offset:96
	v_exp_f32_e32 v116, v116
	v_add_f32_e32 v205, v205, v114
	v_exp_f32_e32 v117, v117
	v_add_f32_e32 v252, v113, v115
	v_exp_f32_e32 v118, v118
	s_waitcnt lgkmcnt(4)
	v_mfma_f32_32x32x16_bf16 v[80:95], v[40:43], v[144:147], v[80:95]
	ds_read_b128 v[40:43], v242 offset:6752
	v_exp_f32_e32 v119, v119
	v_exp_f32_e32 v120, v120
	v_exp_f32_e32 v121, v121
	v_cvt_pk_bf16_f32 v112, v112, v113
	v_cvt_pk_bf16_f32 v113, v114, v115
	v_mfma_f32_32x32x16_bf16 v[96:111], v[44:47], v[144:147], v[96:111]
	ds_read_b128 v[44:47], v242 offset:128
	v_cvt_pk_bf16_f32 v114, v116, v117
	v_cvt_pk_bf16_f32 v115, v118, v119
	v_exp_f32_e32 v122, v122
	v_add_f32_e32 v205, v205, v120
	v_exp_f32_e32 v123, v123
	s_waitcnt lgkmcnt(3)
	v_mfma_f32_32x32x16_bf16 v[80:95], v[238:241], v[140:143], v[80:95]
	ds_read_b128 v[238:241], v242 offset:6784
	v_add_f32_e32 v252, v252, v121
	v_exp_f32_e32 v124, v124
	v_add_f32_e32 v205, v205, v122
	v_exp_f32_e32 v125, v125
	v_add_f32_e32 v252, v252, v123
	v_mfma_f32_32x32x16_bf16 v[96:111], v[32:35], v[140:143], v[96:111]
	ds_read_b128 v[32:35], v242 offset:160
	v_exp_f32_e32 v126, v126
	v_exp_f32_e32 v127, v127
	v_exp_f32_e32 v64, v64
	v_exp_f32_e32 v65, v65
	v_cvt_pk_bf16_f32 v120, v120, v121
	s_waitcnt lgkmcnt(3)
	v_mfma_f32_32x32x16_bf16 v[80:95], v[36:39], v[136:139], v[80:95]
	ds_read_b128 v[36:39], v242 offset:6816
	v_cvt_pk_bf16_f32 v121, v122, v123
	v_cvt_pk_bf16_f32 v122, v124, v125
	v_cvt_pk_bf16_f32 v123, v126, v127
	v_exp_f32_e32 v66, v66
	v_add_f32_e32 v205, v205, v64
	v_mfma_f32_32x32x16_bf16 v[96:111], v[40:43], v[136:139], v[96:111]
	ds_read_b64_tr_b16 v[40:41], v243 offset:13312
	ds_read_b64_tr_b16 v[42:43], v243 offset:14848
	v_exp_f32_e32 v67, v67
	v_add_f32_e32 v252, v252, v65
	v_exp_f32_e32 v68, v68
	v_add_f32_e32 v205, v205, v66
	v_exp_f32_e32 v69, v69
	s_waitcnt lgkmcnt(4)
	v_mfma_f32_32x32x16_bf16 v[80:95], v[44:47], v[132:135], v[80:95]
	ds_read_b64_tr_b16 v[44:45], v243 offset:13376
	ds_read_b64_tr_b16 v[46:47], v243 offset:14912
	v_add_f32_e32 v252, v252, v67
	v_exp_f32_e32 v70, v70
	v_exp_f32_e32 v71, v71
	v_exp_f32_e32 v72, v72
	v_exp_f32_e32 v73, v73
	v_cvt_pk_bf16_f32 v64, v64, v65
	v_mfma_f32_32x32x16_bf16 v[96:111], v[238:241], v[132:135], v[96:111]
	ds_read_b64_tr_b16 v[238:239], v243 offset:16384
	ds_read_b64_tr_b16 v[240:241], v243 offset:17920
	v_cvt_pk_bf16_f32 v65, v66, v67
	v_cvt_pk_bf16_f32 v66, v68, v69
	v_cvt_pk_bf16_f32 v67, v70, v71
	v_exp_f32_e32 v74, v74
	v_add_f32_e32 v205, v205, v72
	v_exp_f32_e32 v75, v75
	s_waitcnt lgkmcnt(6)
	v_mfma_f32_32x32x16_bf16 v[80:95], v[32:35], v[128:131], v[80:95]
	ds_read_b64_tr_b16 v[32:33], v243 offset:16448
	ds_read_b64_tr_b16 v[34:35], v243 offset:17984
	v_add_f32_e32 v252, v252, v73
	v_exp_f32_e32 v76, v76
	v_add_f32_e32 v205, v205, v74
	v_exp_f32_e32 v77, v77
	v_add_f32_e32 v252, v252, v75
	v_exp_f32_e32 v78, v78
	v_mfma_f32_32x32x16_bf16 v[96:111], v[36:39], v[128:131], v[96:111]
	ds_read_b64_tr_b16 v[36:37], v243 offset:19456
	ds_read_b64_tr_b16 v[38:39], v243 offset:20992
	v_exp_f32_e32 v79, v79
	v_cvt_pk_bf16_f32 v72, v72, v73
	v_cvt_pk_bf16_f32 v73, v74, v75
	v_cvt_pk_bf16_f32 v74, v76, v77
	v_cvt_pk_bf16_f32 v75, v78, v79
	s_waitcnt lgkmcnt(6)
	v_mfma_f32_32x32x16_bf16 v[0:15], v[112:115], v[40:43], v[0:15]
	ds_read_b64_tr_b16 v[40:41], v243 offset:19520
	ds_read_b64_tr_b16 v[42:43], v243 offset:21056
	v_add_f32_e32 v205, v205, v116
	v_add_f32_e32 v252, v252, v117
	v_add_f32_e32 v205, v205, v118
	v_add_f32_e32 v252, v252, v119
	v_mfma_f32_32x32x16_bf16 v[16:31], v[112:115], v[44:47], v[16:31]
	ds_read_b64_tr_b16 v[44:45], v243 offset:22528
	ds_read_b64_tr_b16 v[46:47], v243 offset:24064
	v_add_f32_e32 v205, v205, v124
	v_add_f32_e32 v252, v252, v125
	v_add_f32_e32 v205, v205, v126
	v_add_f32_e32 v252, v252, v127
	v_add_u32_e32 v177, s3, v185
	s_waitcnt vmcnt(5)
	ds_write_b128 v177, v[164:167]
	s_waitcnt lgkmcnt(7)
	v_mfma_f32_32x32x16_bf16 v[0:15], v[120:123], v[238:241], v[0:15]
	ds_read_b64_tr_b16 v[238:239], v243 offset:22592
	ds_read_b64_tr_b16 v[240:241], v243 offset:24128
	v_max_f32_e32 v191, v80, v81
	v_max_f32_e32 v178, v96, v97
	v_max3_f32 v191, v191, v82, v83
	v_add_f32_e32 v205, v205, v68
	v_add_f32_e32 v252, v252, v69
	v_add_u32_e32 v177, v177, v181
	s_waitcnt vmcnt(4)
	ds_write_b128 v177, v[172:175]
	v_mfma_f32_32x32x16_bf16 v[16:31], v[120:123], v[32:35], v[16:31]
	v_max3_f32 v178, v178, v98, v99
	v_max3_f32 v191, v191, v84, v85
	v_max3_f32 v178, v178, v100, v101
	v_add_f32_e32 v205, v205, v70
	v_add_f32_e32 v252, v252, v71
	v_mov_b32_e32 v177, s3
	v_cndmask_b32_e64 v177, 0, v177, s[4:5]
	v_add_u32_e32 v177, v214, v177
	s_waitcnt vmcnt(3)
	ds_write_b128 v177, v[168:171]
	v_max3_f32 v191, v191, v86, v87
	v_max3_f32 v178, v178, v102, v103
	v_max3_f32 v191, v191, v88, v89
	v_max3_f32 v178, v178, v104, v105
	v_max3_f32 v191, v191, v90, v91
	v_max3_f32 v178, v178, v106, v107
	v_max3_f32 v191, v191, v92, v93
	v_max3_f32 v178, v178, v108, v109
	v_max3_f32 v191, v191, v94, v95
	v_max3_f32 v178, v178, v110, v111
	v_max_f32_e32 v212, v191, v178
	v_mov_b32_e32 v253, v212
	v_add_f32_e32 v205, v205, v76
	v_add_f32_e32 v252, v252, v77
	v_add_f32_e32 v205, v205, v78
	v_add_f32_e32 v252, v252, v79
	v_add_f32_e32 v205, v205, v252
	s_nop 1
	v_permlane32_swap_b32_e32 v212, v253
	v_max_f32_e32 v212, v212, v253
	v_cmp_lt_f32_e32 vcc, s58, v212
	s_cbranch_vccnz .Lmla_skip_b_ool

; __device__ __forceinline__ void mla_attn_phase(LAS unsigned char* lds, const bf16_t* q, const bf16_t* kv, const bf16_t* krope, const bf16_t* projb, bf16_t* y, int unit0, int G, int nu) {
;     ...
; #pragma unroll 1
;     for (int t = 0; t < 62; t += 2) {
;         MLA_ITER(t, c0, c1, n0, n1, sa0, sa1, sa2, sb0, sb1, sb2, false);
;         MLA_ITER(t + 1, n0, n1, c0, c1, sb0, sb1, sb2, sa0, sa1, sa2, true);
;     }
;     MLA_ITER(62, c0, c1, n0, n1, sa0, sa1, sa2, sb0, sb1, sb2, false);
;     MLA_EXP(n0, n1);
;     MLA_PV(lds + sl_c + MLA_KB);
.Lmla_skip_b_ool:
	s_waitcnt lgkmcnt(0)
	v_mfma_f32_32x32x16_bf16 v[0:15], v[64:67], v[36:39], v[0:15]
	v_mfma_f32_32x32x16_bf16 v[16:31], v[64:67], v[40:43], v[16:31]
	v_mfma_f32_32x32x16_bf16 v[0:15], v[72:75], v[44:47], v[0:15]
	v_mfma_f32_32x32x16_bf16 v[16:31], v[72:75], v[238:241], v[16:31]
	s_nop 1
	v_cndmask_b32_e32 v68, 0, v212, vcc
	v_exp_f32_e64 v70, -v68
	v_add_f32_e32 v203, v203, v68
	v_xor_b32_e32 v69, 0x80000000, v203
	ds_bpermute_b32 v116, v217, v70
	ds_bpermute_b32 v117, v218, v70
	ds_bpermute_b32 v118, v219, v70
	ds_bpermute_b32 v119, v220, v70
	ds_bpermute_b32 v120, v221, v70
	ds_bpermute_b32 v121, v222, v70
	ds_bpermute_b32 v122, v223, v70
	ds_bpermute_b32 v123, v224, v70
	ds_bpermute_b32 v124, v225, v70
	ds_bpermute_b32 v125, v226, v70
	ds_bpermute_b32 v126, v227, v70
	ds_bpermute_b32 v127, v228, v70
	ds_bpermute_b32 v64, v229, v70
	ds_bpermute_b32 v65, v230, v70
	ds_bpermute_b32 v66, v231, v70
	ds_bpermute_b32 v67, v232, v70
	v_sub_f32_e32 v80, v80, v68
	v_sub_f32_e32 v81, v81, v68
	v_sub_f32_e32 v82, v82, v68
	v_sub_f32_e32 v83, v83, v68
	v_sub_f32_e32 v84, v84, v68
	v_sub_f32_e32 v85, v85, v68
	v_sub_f32_e32 v86, v86, v68
	v_sub_f32_e32 v87, v87, v68
	v_sub_f32_e32 v88, v88, v68
	v_sub_f32_e32 v89, v89, v68
	v_sub_f32_e32 v90, v90, v68
	v_sub_f32_e32 v91, v91, v68
	v_sub_f32_e32 v92, v92, v68
	v_sub_f32_e32 v93, v93, v68
	v_sub_f32_e32 v94, v94, v68
	v_sub_f32_e32 v95, v95, v68
	v_sub_f32_e32 v96, v96, v68
	v_sub_f32_e32 v97, v97, v68
	v_sub_f32_e32 v98, v98, v68
	v_sub_f32_e32 v99, v99, v68
	v_sub_f32_e32 v100, v100, v68
	v_sub_f32_e32 v101, v101, v68
	v_sub_f32_e32 v102, v102, v68
	v_sub_f32_e32 v103, v103, v68
	v_sub_f32_e32 v104, v104, v68
	v_sub_f32_e32 v105, v105, v68
	v_sub_f32_e32 v106, v106, v68
	v_sub_f32_e32 v107, v107, v68
	v_sub_f32_e32 v108, v108, v68
	v_sub_f32_e32 v109, v109, v68
	v_sub_f32_e32 v110, v110, v68
	v_sub_f32_e32 v111, v111, v68
	v_mul_f32_e32 v205, v205, v70
	v_mov_b32_e32 v48, v69
	v_mov_b32_e32 v49, v69
	v_mov_b32_e32 v50, v69
	v_mov_b32_e32 v51, v69
	v_mov_b32_e32 v52, v69
	v_mov_b32_e32 v53, v69
	v_mov_b32_e32 v54, v69
	v_mov_b32_e32 v55, v69
	v_mov_b32_e32 v56, v69
	v_mov_b32_e32 v57, v69
	v_mov_b32_e32 v58, v69
	v_mov_b32_e32 v59, v69
	v_mov_b32_e32 v60, v69
	v_mov_b32_e32 v61, v69
	v_mov_b32_e32 v62, v69
	v_mov_b32_e32 v63, v69
	s_waitcnt lgkmcnt(0)
	v_pk_mul_f32 v[0:1], v[0:1], v[116:117]
	v_pk_mul_f32 v[16:17], v[16:17], v[116:117]
	v_pk_mul_f32 v[2:3], v[2:3], v[118:119]
	v_pk_mul_f32 v[18:19], v[18:19], v[118:119]
	v_pk_mul_f32 v[4:5], v[4:5], v[120:121]
	v_pk_mul_f32 v[20:21], v[20:21], v[120:121]
	v_pk_mul_f32 v[6:7], v[6:7], v[122:123]
	v_pk_mul_f32 v[22:23], v[22:23], v[122:123]
	v_pk_mul_f32 v[8:9], v[8:9], v[124:125]
	v_pk_mul_f32 v[24:25], v[24:25], v[124:125]
	v_pk_mul_f32 v[10:11], v[10:11], v[126:127]
	v_pk_mul_f32 v[26:27], v[26:27], v[126:127]
	v_pk_mul_f32 v[12:13], v[12:13], v[64:65]
	v_pk_mul_f32 v[28:29], v[28:29], v[64:65]
	v_pk_mul_f32 v[14:15], v[14:15], v[66:67]
	v_pk_mul_f32 v[30:31], v[30:31], v[66:67]
	v_mov_b32_e32 v64, 0
	v_mov_b32_e32 v65, 0
	v_mov_b32_e32 v66, 0
	v_mov_b32_e32 v67, 0
	v_mov_b32_e32 v72, 0
	v_mov_b32_e32 v73, 0
	v_mov_b32_e32 v74, 0
	v_mov_b32_e32 v75, 0
	s_branch .Lmla_skip_b
.LBB0_209:
	v_mfma_f32_32x32x16_bf16 v[0:15], v[64:67], v[36:39], v[0:15]
	v_mfma_f32_32x32x16_bf16 v[16:31], v[64:67], v[40:43], v[16:31]
	v_mfma_f32_32x32x16_bf16 v[0:15], v[72:75], v[44:47], v[0:15]
	v_mfma_f32_32x32x16_bf16 v[16:31], v[72:75], v[238:241], v[16:31]
	v_mov_b64_e32 v[32:33], v[48:49]
	v_mov_b64_e32 v[34:35], v[50:51]
	v_mov_b64_e32 v[36:37], v[52:53]
	v_mov_b64_e32 v[38:39], v[54:55]
	v_mov_b64_e32 v[40:41], v[56:57]
	v_mov_b64_e32 v[42:43], v[58:59]
	v_mov_b64_e32 v[44:45], v[60:61]
	v_mov_b64_e32 v[46:47], v[62:63]
	ds_read_b128 v[64:67], v249
	ds_read_b128 v[68:71], v249 offset:32
	v_exp_f32_e32 v178, v81
	v_exp_f32_e32 v112, v97
	s_waitcnt lgkmcnt(1)
	v_mfma_f32_32x32x16_bf16 v[48:63], v[64:67], v[148:151], v[32:47]
	ds_read_b128 v[64:67], v248
	ds_read_b128 v[72:75], v248 offset:32
	s_waitcnt lgkmcnt(1)
	v_mfma_f32_32x32x16_bf16 v[32:47], v[64:67], v[148:151], v[32:47]
	s_waitcnt lgkmcnt(0)
	v_mfma_f32_32x32x16_bf16 v[32:47], v[72:75], v[144:147], v[32:47]
	v_exp_f32_e32 v73, v104
	v_exp_f32_e32 v104, v109
	v_exp_f32_e32 v74, v90
	v_exp_f32_e32 v75, v106
	v_exp_f32_e32 v90, v91
	v_exp_f32_e32 v72, v88
	v_exp_f32_e32 v88, v89
	v_mfma_f32_32x32x16_bf16 v[48:63], v[68:71], v[144:147], v[48:63]
	ds_read_b128 v[64:67], v248 offset:64
	ds_read_b128 v[68:71], v249 offset:64
	v_exp_f32_e32 v89, v110
	v_exp_f32_e32 v106, v111
	s_waitcnt lgkmcnt(1)
	v_mfma_f32_32x32x16_bf16 v[32:47], v[64:67], v[140:143], v[32:47]
	s_waitcnt lgkmcnt(0)
	v_mfma_f32_32x32x16_bf16 v[48:63], v[68:71], v[140:143], v[48:63]
	ds_read_b128 v[64:67], v248 offset:96
	ds_read_b128 v[68:71], v249 offset:96
	s_waitcnt lgkmcnt(1)
	v_mfma_f32_32x32x16_bf16 v[32:47], v[64:67], v[136:139], v[32:47]
	s_waitcnt lgkmcnt(0)
	v_mfma_f32_32x32x16_bf16 v[48:63], v[68:71], v[136:139], v[48:63]
	ds_read_b128 v[64:67], v248 offset:128
	ds_read_b128 v[68:71], v249 offset:128
	s_waitcnt lgkmcnt(1)
	v_mfma_f32_32x32x16_bf16 v[32:47], v[64:67], v[132:135], v[32:47]
	s_waitcnt lgkmcnt(0)
	v_mfma_f32_32x32x16_bf16 v[48:63], v[68:71], v[132:135], v[48:63]
	ds_read_b128 v[64:67], v248 offset:160
	ds_read_b128 v[68:71], v249 offset:160
	s_waitcnt lgkmcnt(1)
	v_mfma_f32_32x32x16_bf16 v[32:47], v[64:67], v[128:131], v[32:47]
	v_exp_f32_e32 v64, v80
	v_exp_f32_e32 v65, v96
	v_exp_f32_e32 v66, v82
	v_exp_f32_e32 v67, v98
	v_exp_f32_e32 v82, v83
	v_exp_f32_e32 v83, v92
	v_exp_f32_e32 v92, v93
	s_waitcnt lgkmcnt(0)
; __device__ __forceinline__ void mla_attn_phase(LAS unsigned char* lds, const bf16_t* q, const bf16_t* kv, const bf16_t* krope, const bf16_t* projb, bf16_t* y, int unit0, int G, int nu) {
;     ...
;     MLA_ITER(62, c0, c1, n0, n1, sa0, sa1, sa2, sb0, sb1, sb2, false);
;     MLA_EXP(n0, n1);
	v_mfma_f32_32x32x16_bf16 v[48:63], v[68:71], v[128:131], v[48:63]
	v_exp_f32_e32 v68, v84
	v_exp_f32_e32 v84, v85
	v_exp_f32_e32 v70, v86
	v_exp_f32_e32 v71, v102
	v_exp_f32_e32 v86, v87
	v_exp_f32_e32 v85, v108
	v_add_f32_e32 v113, v65, v64
	v_exp_f32_e32 v80, v99
	v_pk_add_f32 v[108:109], v[112:113], v[178:179]
	v_exp_f32_e32 v69, v100
	v_exp_f32_e32 v96, v101
	v_pk_add_f32 v[108:109], v[108:109], v[108:109] op_sel_hi:[0,1]
	v_add_f32_e32 v81, v67, v66
	v_add_f32_e32 v99, v71, v70
	v_exp_f32_e32 v100, v105
	v_add_f32_e32 v105, v85, v83
	v_cvt_pk_bf16_f32 v79, v70, v86
	v_cvt_pk_bf16_f32 v70, v83, v92
	v_mov_b32_e32 v83, v109
	v_cvt_pk_bf16_f32 v76, v64, v178
	v_cvt_pk_bf16_f32 v64, v65, v112
	v_cvt_pk_bf16_f32 v65, v67, v80
	v_pk_add_f32 v[80:81], v[80:81], v[82:83]
	v_exp_f32_e32 v98, v103
	v_exp_f32_e32 v87, v94
	v_exp_f32_e32 v94, v95
	v_pk_add_f32 v[80:81], v[80:81], v[80:81] op_sel_hi:[0,1]
	v_add_f32_e32 v97, v69, v68
	v_add_f32_e32 v103, v75, v74
	v_cvt_pk_bf16_f32 v77, v66, v82
	v_cvt_pk_bf16_f32 v66, v69, v96
	v_cvt_pk_bf16_f32 v69, v74, v90
	v_cvt_pk_bf16_f32 v74, v85, v104
	v_mov_b32_e32 v85, v81
	v_pk_add_f32 v[80:81], v[96:97], v[84:85]
	v_exp_f32_e32 v102, v107
	v_pk_add_f32 v[80:81], v[80:81], v[80:81] op_sel_hi:[0,1]
	v_add_f32_e32 v107, v89, v87
	v_cvt_pk_bf16_f32 v67, v71, v98
	v_cvt_pk_bf16_f32 v71, v87, v94
	v_mov_b32_e32 v87, v81
	v_pk_add_f32 v[80:81], v[98:99], v[86:87]
	v_add_f32_e32 v101, v73, v72
	v_pk_add_f32 v[80:81], v[80:81], v[80:81] op_sel_hi:[0,1]
	v_cvt_pk_bf16_f32 v78, v68, v84
	v_cvt_pk_bf16_f32 v68, v72, v88
	v_cvt_pk_bf16_f32 v72, v73, v100
	v_cvt_pk_bf16_f32 v73, v75, v102
	v_cvt_pk_bf16_f32 v75, v89, v106
	v_mov_b32_e32 v89, v81
	v_pk_add_f32 v[80:81], v[100:101], v[88:89]
	s_nop 0
	v_pk_add_f32 v[80:81], v[80:81], v[80:81] op_sel_hi:[0,1]
	v_mov_b32_e32 v91, v81
	v_pk_add_f32 v[80:81], v[102:103], v[90:91]
	s_nop 0
	v_pk_add_f32 v[80:81], v[80:81], v[80:81] op_sel_hi:[0,1]
	v_mov_b32_e32 v93, v81
	v_pk_add_f32 v[80:81], v[104:105], v[92:93]
	s_nop 0
	v_pk_add_f32 v[80:81], v[80:81], v[80:81] op_sel_hi:[0,1]
	v_mov_b32_e32 v95, v81
	v_pk_add_f32 v[80:81], v[106:107], v[94:95]
	s_nop 0
	v_add_f32_e32 v100, v80, v81
	ds_read_b64_tr_b16 v[80:81], v233 offset:64512
	ds_read_b64_tr_b16 v[82:83], v234 offset:1536
	ds_read_b64_tr_b16 v[84:85], v233 offset:64576
	ds_read_b64_tr_b16 v[86:87], v234 offset:1600
	s_waitcnt lgkmcnt(0)
	v_mfma_f32_32x32x16_bf16 v[16:31], v[76:79], v[84:87], v[16:31]
	ds_read_b64_tr_b16 v[84:85], v234 offset:3072
	ds_read_b64_tr_b16 v[86:87], v234 offset:4608
	ds_read_b64_tr_b16 v[88:89], v234 offset:3136
	ds_read_b64_tr_b16 v[90:91], v234 offset:4672
	v_mfma_f32_32x32x16_bf16 v[0:15], v[76:79], v[80:83], v[0:15]
	s_waitcnt lgkmcnt(0)
	v_mfma_f32_32x32x16_bf16 v[16:31], v[68:71], v[88:91], v[16:31]
	ds_read_b64_tr_b16 v[88:89], v234 offset:6144
	ds_read_b64_tr_b16 v[90:91], v234 offset:7680
	ds_read_b64_tr_b16 v[92:93], v234 offset:6208
	ds_read_b64_tr_b16 v[94:95], v234 offset:7744
	v_mfma_f32_32x32x16_bf16 v[0:15], v[68:71], v[84:87], v[0:15]
	s_waitcnt lgkmcnt(0)
	v_mfma_f32_32x32x16_bf16 v[16:31], v[64:67], v[92:95], v[16:31]
	ds_read_b64_tr_b16 v[92:93], v234 offset:9216
	ds_read_b64_tr_b16 v[94:95], v234 offset:10752
	ds_read_b64_tr_b16 v[96:97], v234 offset:9280
	ds_read_b64_tr_b16 v[98:99], v234 offset:10816
	v_mfma_f32_32x32x16_bf16 v[0:15], v[64:67], v[88:91], v[0:15]
	v_add_f32_e32 v64, v205, v100
	s_waitcnt lgkmcnt(0)
	v_mfma_f32_32x32x16_bf16 v[16:31], v[72:75], v[96:99], v[16:31]
	v_max_f32_e32 v96, v49, v49
	v_max_f32_e32 v97, v48, v48
	v_max_f32_e32 v96, v97, v96
	v_max3_f32 v97, v50, v51, v33
	v_max3_f32 v96, v96, v32, v34
	v_max3_f32 v96, v96, v35, v52
	v_max3_f32 v97, v97, v54, v55
	v_max3_f32 v96, v96, v53, v36
	v_max3_f32 v97, v97, v38, v39
	v_max3_f32 v96, v96, v37, v56
	v_max3_f32 v97, v97, v58, v59
	v_max3_f32 v96, v96, v57, v40
	v_max3_f32 v97, v97, v42, v43
	v_max3_f32 v96, v96, v41, v60
	v_max3_f32 v97, v97, v62, v63
	v_mfma_f32_32x32x16_bf16 v[0:15], v[72:75], v[92:95], v[0:15]
	v_max3_f32 v96, v96, v61, v44
	v_max3_f32 v97, v97, v46, v47
	v_max3_f32 v65, v96, v45, v97
	v_mov_b32_e32 v66, v65
	s_nop 1
	v_permlane32_swap_b32_e32 v65, v66
	v_max_f32_e32 v66, v66, v66
	v_max_f32_e32 v65, v65, v65
	v_max_f32_e32 v65, v65, v66
	v_cmp_lt_f32_e32 vcc, s58, v65
	s_cbranch_vccz .LBB0_200
	s_nop 0
	v_cndmask_b32_e32 v66, 0, v65, vcc
	v_exp_f32_e64 v65, -v66
	v_pk_add_f32 v[48:49], v[48:49], v[66:67] op_sel_hi:[1,0] neg_lo:[0,1] neg_hi:[0,1]
	v_pk_add_f32 v[32:33], v[32:33], v[66:67] op_sel_hi:[1,0] neg_lo:[0,1] neg_hi:[0,1]
	v_pk_add_f32 v[50:51], v[50:51], v[66:67] op_sel_hi:[1,0] neg_lo:[0,1] neg_hi:[0,1]
	ds_bpermute_b32 v68, v217, v65
	ds_bpermute_b32 v69, v218, v65
	ds_bpermute_b32 v70, v219, v65
	ds_bpermute_b32 v71, v220, v65
	ds_bpermute_b32 v72, v221, v65
	ds_bpermute_b32 v73, v222, v65
	ds_bpermute_b32 v74, v223, v65
	ds_bpermute_b32 v75, v224, v65
	ds_bpermute_b32 v76, v225, v65
	ds_bpermute_b32 v77, v226, v65
	ds_bpermute_b32 v78, v227, v65
	ds_bpermute_b32 v79, v228, v65
	ds_bpermute_b32 v80, v229, v65
	ds_bpermute_b32 v82, v231, v65
	ds_bpermute_b32 v83, v232, v65
	ds_bpermute_b32 v81, v230, v65
	v_pk_add_f32 v[34:35], v[34:35], v[66:67] op_sel_hi:[1,0] neg_lo:[0,1] neg_hi:[0,1]
	v_pk_add_f32 v[52:53], v[52:53], v[66:67] op_sel_hi:[1,0] neg_lo:[0,1] neg_hi:[0,1]
	v_pk_add_f32 v[36:37], v[36:37], v[66:67] op_sel_hi:[1,0] neg_lo:[0,1] neg_hi:[0,1]
	v_pk_add_f32 v[54:55], v[54:55], v[66:67] op_sel_hi:[1,0] neg_lo:[0,1] neg_hi:[0,1]
	v_pk_add_f32 v[38:39], v[38:39], v[66:67] op_sel_hi:[1,0] neg_lo:[0,1] neg_hi:[0,1]
	v_pk_add_f32 v[56:57], v[56:57], v[66:67] op_sel_hi:[1,0] neg_lo:[0,1] neg_hi:[0,1]
	v_pk_add_f32 v[40:41], v[40:41], v[66:67] op_sel_hi:[1,0] neg_lo:[0,1] neg_hi:[0,1]
	v_pk_add_f32 v[58:59], v[58:59], v[66:67] op_sel_hi:[1,0] neg_lo:[0,1] neg_hi:[0,1]
	v_pk_add_f32 v[42:43], v[42:43], v[66:67] op_sel_hi:[1,0] neg_lo:[0,1] neg_hi:[0,1]
	v_pk_add_f32 v[60:61], v[60:61], v[66:67] op_sel_hi:[1,0] neg_lo:[0,1] neg_hi:[0,1]
	v_pk_add_f32 v[44:45], v[44:45], v[66:67] op_sel_hi:[1,0] neg_lo:[0,1] neg_hi:[0,1]
	s_waitcnt lgkmcnt(1)
	v_pk_mul_f32 v[14:15], v[14:15], v[82:83]
	s_waitcnt lgkmcnt(0)
	v_pk_mul_f32 v[12:13], v[12:13], v[80:81]
	v_pk_mul_f32 v[10:11], v[10:11], v[78:79]
	v_pk_mul_f32 v[8:9], v[8:9], v[76:77]
	v_pk_mul_f32 v[6:7], v[6:7], v[74:75]
	v_pk_mul_f32 v[4:5], v[4:5], v[72:73]
	v_pk_mul_f32 v[2:3], v[2:3], v[70:71]
	v_pk_mul_f32 v[0:1], v[0:1], v[68:69]
	v_pk_mul_f32 v[30:31], v[30:31], v[82:83]
	v_pk_mul_f32 v[28:29], v[28:29], v[80:81]
	v_pk_mul_f32 v[26:27], v[26:27], v[78:79]
	v_pk_mul_f32 v[24:25], v[24:25], v[76:77]
	v_pk_mul_f32 v[22:23], v[22:23], v[74:75]
	v_pk_mul_f32 v[20:21], v[20:21], v[72:73]
	v_pk_mul_f32 v[18:19], v[18:19], v[70:71]
	v_pk_mul_f32 v[16:17], v[16:17], v[68:69]
	v_pk_add_f32 v[62:63], v[62:63], v[66:67] op_sel_hi:[1,0] neg_lo:[0,1] neg_hi:[0,1]
	v_pk_add_f32 v[46:47], v[46:47], v[66:67] op_sel_hi:[1,0] neg_lo:[0,1] neg_hi:[0,1]
	v_mul_f32_e32 v64, v64, v65
	s_branch .LBB0_200
